# scan small-piece loader: U0+Y0 and V+d gathered by two LDS-DMA instructions per chunk instead of four
# baseline (speedup 1.0000x reference)
; #define SP_BAR() asm volatile("s_waitcnt lgkmcnt(0)\n\ts_barrier" ::: "memory")
; #define SP_WAIT() asm volatile("s_waitcnt vmcnt(36)" ::: "memory")
; __device__ __forceinline__ void rw_dma_init(const Args& a, DmaPtrs& P, int head, int ib, int lw, int lane) {
;     const unsigned char* outb = (const unsigned char*)a.out; const unsigned char* ws = a.ws; const size_t c0 = (size_t)head * 2048;
;     if (lw == 0) { P.p[0] = outb + OUT_W1A + c0 + lane * 16; P.p[1] = P.p[0] + 1024; P.p[2] = outb + OUT_QA + c0 + lane * 16; P.p[3] = P.p[2] + 1024; P.off[0] = 0u; P.off[1] = 1024u; P.off[2] = 2048u; P.off[3] = 3072u; }
;     else if (lw == 1) { P.p[0] = outb + OUT_BT + c0 + lane * 16; P.p[1] = P.p[0] + 1024; P.p[2] = outb + OUT_KT + c0 + lane * 16; P.p[3] = P.p[2] + 1024; P.off[0] = 4096u; P.off[1] = 5120u; P.off[2] = 6144u; P.off[3] = 7168u; }
;     else { const int l32 = lane & 31; P.p[0] = ws + WS_U0 + c0 + ib * 512 + l32 * 16; P.p[1] = ws + WS_Y0 + c0 + ib * 512 + l32 * 16; P.p[2] = ws + WS_VS + c0 + ib * 512 + l32 * 16; P.p[3] = ws + WS_DD + (size_t)head * 256 + (lane & 15) * 16;
;            P.off[0] = 8192u; P.off[1] = 8704u; P.off[2] = 9216u; P.off[3] = 9728u; }
; }
; __device__ __forceinline__ void rw_dma_issue(DmaPtrs& P, int lw, int lane, unsigned slot_lds) {
;     if (lw < 2) {
; #pragma unroll
;         for (int q = 0; q < 4; ++q) attn_body::glds16(P.p[q], (unsigned)__builtin_amdgcn_readfirstlane(slot_lds + P.off[q]));
;     } else {
;         if (lane < 32) {
; #pragma unroll
;             for (int q = 0; q < 3; ++q) attn_body::glds16(P.p[q], (unsigned)__builtin_amdgcn_readfirstlane(slot_lds + P.off[q])); }
;         if (lane < 16) attn_body::glds16(P.p[3], (unsigned)__builtin_amdgcn_readfirstlane(slot_lds + P.off[3]));
;     }
; #pragma unroll
;     for (int q = 0; q < 4; ++q) P.p[q] += (lw == 2 && q == 3) ? 16 * 256 : 16 * 2048;
; }
; __device__ __forceinline__ void p3_rwkv_state(Frame& F, const Args& a) {
;     ...
;     if (loader) {
;         DmaPtrs P; rw_dma_init(a, P, head, ib, lw, lane);
;         for (int n = 0; n < SP_D; ++n) rw_dma_issue(P, lw, lane, lds0 + (unsigned)(n % SP_R) * SP_SLOT);
;         SP_WAIT();
;         SP_BAR();
.Lscan_ldsmall:
	s_lshl_b32 s2, s0, 11
	s_lshl_b32 s5, s4, 9
	s_add_u32 s2, s2, s5
	s_add_u32 s12, s90, s2
	s_addc_u32 s13, s91, 0
	v_and_b32_e32 v0, 31, v76
	v_lshlrev_b32_e32 v0, 4, v0
	v_mov_b32_e32 v1, 0
	v_lshl_add_u64 v[0:1], s[12:13], 0, v[0:1]
	s_mov_b64 s[2:3], 0x19000000
	v_lshl_add_u64 v[2:3], v[0:1], 0, s[2:3]
	s_mov_b64 s[2:3], 0x1b000000
	v_lshl_add_u64 v[4:5], v[0:1], 0, s[2:3]
	s_mov_b64 s[2:3], 0x1cfffc00
	v_lshl_add_u64 v[6:7], v[0:1], 0, s[2:3]
	s_lshl_b32 s2, s0, 8
	s_add_u32 s12, s90, s2
	s_addc_u32 s13, s91, 0
	v_and_b32_e32 v8, 15, v76
	v_lshlrev_b32_e32 v8, 4, v8
	v_mov_b32_e32 v9, 0
	v_lshl_add_u64 v[8:9], s[12:13], 0, v[8:9]
	s_mov_b64 s[2:3], 0x1efffc00
	v_lshl_add_u64 v[8:9], v[8:9], 0, s[2:3]
	v_cmp_gt_u32_e32 vcc, 32, v76
	s_nop 1
	v_cndmask_b32_e32 v2, v4, v2, vcc
	v_cndmask_b32_e32 v3, v5, v3, vcc
	v_cndmask_b32_e32 v6, v8, v6, vcc
	v_cndmask_b32_e32 v7, v9, v7, vcc
	v_mov_b32_e32 v10, 0x1000
	v_mov_b32_e32 v12, 0x8000
	v_cndmask_b32_e32 v10, v10, v12, vcc
	v_mov_b32_e32 v11, 0
	s_mov_b64 s[6:7], 0x8000
	s_mov_b32 s15, 0
	s_mov_b32 s18, 0
.Lscan_ldsmall_pro:
	s_add_i32 s16, s15, 0x2000
	s_mov_b32 m0, s16
	s_add_i32 s15, s15, 0x2800
	global_load_lds_dwordx4 v[2:3], off
	s_mov_b32 exec_hi, 0xffff
	s_cmp_eq_u32 s15, 0x25800
	global_load_lds_dwordx4 v[6:7], off offset:1024
	s_mov_b64 exec, -1
	s_cselect_b32 s15, 0, s15
	v_lshl_add_u64 v[2:3], v[2:3], 0, s[6:7]
	v_lshl_add_u64 v[6:7], v[6:7], 0, v[10:11]
	s_add_i32 s18, s18, 1
	s_cmp_lt_u32 s18, 12
	s_cbranch_scc1 .Lscan_ldsmall_pro
	s_waitcnt vmcnt(18)
	s_barrier
	s_mov_b32 s18, 0
	s_movk_i32 s17, 0x100

; #define SP_BAR() asm volatile("s_waitcnt lgkmcnt(0)\n\ts_barrier" ::: "memory")
; #define SP_WAIT() asm volatile("s_waitcnt vmcnt(36)" ::: "memory")
; __device__ __forceinline__ void rw_dma_issue(DmaPtrs& P, int lw, int lane, unsigned slot_lds) {
;     if (lw < 2) {
; #pragma unroll
;         for (int q = 0; q < 4; ++q) attn_body::glds16(P.p[q], (unsigned)__builtin_amdgcn_readfirstlane(slot_lds + P.off[q]));
;     } else {
;         if (lane < 32) {
; #pragma unroll
;             for (int q = 0; q < 3; ++q) attn_body::glds16(P.p[q], (unsigned)__builtin_amdgcn_readfirstlane(slot_lds + P.off[q])); }
;         if (lane < 16) attn_body::glds16(P.p[3], (unsigned)__builtin_amdgcn_readfirstlane(slot_lds + P.off[3]));
;     }
; #pragma unroll
;     for (int q = 0; q < 4; ++q) P.p[q] += (lw == 2 && q == 3) ? 16 * 256 : 16 * 2048;
; }
; __device__ __forceinline__ void p3_rwkv_state(Frame& F, const Args& a) {
;     ...
;         for (int n = 0; n < NC; n += 2) {
;             if (n + SP_D + 1 < NC) { rw_dma_issue(P, lw, lane, lds0 + (unsigned)((n + SP_D) % SP_R) * SP_SLOT); rw_dma_issue(P, lw, lane, lds0 + (unsigned)((n + SP_D + 1) % SP_R) * SP_SLOT); SP_WAIT(); }
;             else asm volatile("s_waitcnt vmcnt(0)" ::: "memory");
;             SP_BAR();
.Lscan_ldsmall_go:
	s_add_i32 s16, s15, 0x2000
	s_mov_b32 m0, s16
	s_add_i32 s15, s15, 0x2800
	global_load_lds_dwordx4 v[2:3], off
	s_mov_b32 exec_hi, 0xffff
	s_cmp_eq_u32 s15, 0x25800
	global_load_lds_dwordx4 v[6:7], off offset:1024
	s_mov_b64 exec, -1
	s_cselect_b32 s15, 0, s15
	v_lshl_add_u64 v[2:3], v[2:3], 0, s[6:7]
	v_lshl_add_u64 v[6:7], v[6:7], 0, v[10:11]
	s_add_i32 s16, s15, 0x2000
	s_mov_b32 m0, s16
	s_add_i32 s15, s15, 0x2800
	global_load_lds_dwordx4 v[2:3], off
	s_mov_b32 exec_hi, 0xffff
	s_cmp_eq_u32 s15, 0x25800
	global_load_lds_dwordx4 v[6:7], off offset:1024
	s_mov_b64 exec, -1
	s_cselect_b32 s15, 0, s15
	v_lshl_add_u64 v[2:3], v[2:3], 0, s[6:7]
	v_lshl_add_u64 v[6:7], v[6:7], 0, v[10:11]
	s_waitcnt vmcnt(18)
	s_branch .Lscan_ldsmall_bar
